# attention: L2 warm-up of the unit's ZS gate tile after the third tile (dummy dword loads), on top of the vote skip
# baseline (speedup 1.0000x reference)
; __device__ __forceinline__ int lane_id() { return (int)__builtin_amdgcn_mbcnt_hi(~0u, __builtin_amdgcn_mbcnt_lo(~0u, 0u)); }
; #define LAS __attribute__((address_space(3)))
; __device__ __forceinline__ void attn_unit(LAS unsigned char* lds, const int wid, int b, int h, int qb, const bf16_t* __restrict__ Q, const bf16_t* __restrict__ K,
;                                           const bf16_t* __restrict__ V, const bf16_t* __restrict__ ZS, bf16_t* __restrict__ OG) {
;     ...
;         prev_valid = valid;
;         asm volatile("s_waitcnt vmcnt(0)" ::: "memory");
;         __syncthreads();
;     ...
;         int lane_e = lane_id(); asm volatile("" : "+v"(lane_e));
;         const int r32e = lane_e & 31, hie = lane_e >> 5, rowq = lane_e >> 3, c8 = (lane_e & 7) * 8;
;         LAS float* stg = (LAS float*)(lds + 81920 + wid * 8192);
;         const size_t gbase = (tok0 + qw0) * DM + h * HD + c8;
;         u32x4 zv[2][4];
; #pragma unroll
;         for (int ps = 0; ps < 2; ++ps)
; #pragma unroll
;             for (int j = 0; j < 4; ++j) zv[ps][j] = *(const u32x4*)(ZS + gbase + (size_t)(8 * j + rowq) * DM + 64 * ps);
.LBB0_609:
	s_waitcnt vmcnt(0)
	s_xor_b32 s67, s67, 1
	s_add_i32 s42, s42, -1
	s_sub_i32 s65, s65, 64
	v_cmp_gt_f32_e32 vcc, 0x43000000, v158
	s_lshr_b32 s98, s54, 3
	s_lshl_b32 s99, s67, 5
	s_add_i32 s98, s98, s99
	s_add_i32 s98, s98, 0x24000
	s_cmp_lg_u64 vcc, 0
	s_cselect_b32 s99, 1, 0
	s_xor_b32 s75, s99, 1
	s_add_i32 s74, s74, s75
	v_mov_b32_e32 v80, s98
	v_mov_b32_e32 v81, s99
	s_mov_b64 s[100:101], exec
	s_mov_b64 exec, 1
	ds_write_b32 v80, v81
	s_mov_b64 exec, s[100:101]
	s_cmpk_lg_i32 s65, 0xffc0
	s_waitcnt vmcnt(0) lgkmcnt(0)
	s_barrier
	s_cbranch_scc0 .LBB0_611
	s_add_i32 s32, s32, 1
	s_cmp_lt_u32 s32, 5
	s_cbranch_scc0 .Lvote_do_a
	s_cmp_lg_u32 s32, 3
	s_cbranch_scc1 .Lvote_skip_a
	s_add_u32 s98, s50, s64
	s_addc_u32 s99, s51, 0
	s_lshl_b64 s[98:99], s[98:99], 11
	v_lshlrev_b32_e32 v244, 3, v195
	v_and_b32_e32 v244, 56, v244
	v_or_b32_e32 v244, s98, v244
	v_or_b32_e32 v244, s62, v244
	v_mov_b32_e32 v245, s99
	v_lshlrev_b64 v[244:245], 1, v[244:245]
	v_lshl_add_u64 v[244:245], s[46:47], 0, v[244:245]
	v_ashrrev_i32_e32 v246, 3, v195
	v_mov_b32_e32 v247, 0
	v_lshlrev_b64 v[246:247], 12, v[246:247]
	v_lshl_add_u64 v[244:245], v[244:245], 0, v[246:247]
	s_mov_b32 s100, 0x8000
	s_mov_b32 s101, 0
	global_load_dword v236, v[244:245], off
	global_load_dword v237, v[244:245], off offset:128
	v_lshl_add_u64 v[244:245], v[244:245], 0, s[100:101]
	global_load_dword v238, v[244:245], off
	global_load_dword v239, v[244:245], off offset:128
	v_lshl_add_u64 v[244:245], v[244:245], 0, s[100:101]
	global_load_dword v240, v[244:245], off
	global_load_dword v241, v[244:245], off offset:128
	v_lshl_add_u64 v[244:245], v[244:245], 0, s[100:101]
	global_load_dword v242, v[244:245], off
	global_load_dword v243, v[244:245], off offset:128
	s_branch .Lvote_skip_a
.Lvote_do_a:
	s_lshl_b32 s98, s67, 5
	s_add_i32 s98, s98, 0x24000
	v_mov_b32_e32 v80, s98
	ds_read_b128 v[84:87], v80
	ds_read_b128 v[88:91], v80 offset:16
	s_waitcnt lgkmcnt(0)
	v_or3_b32 v84, v84, v85, v86
	v_or3_b32 v88, v88, v89, v90
	v_or3_b32 v84, v84, v87, v91
	v_or_b32_e32 v84, v84, v88
	s_nop 0
	v_readfirstlane_b32 s99, v84
	s_cmp_eq_u32 s99, 0
	s_cbranch_scc1 .LBB0_611

; __device__ __forceinline__ int lane_id() { return (int)__builtin_amdgcn_mbcnt_hi(~0u, __builtin_amdgcn_mbcnt_lo(~0u, 0u)); }
; #define LAS __attribute__((address_space(3)))
; __device__ __forceinline__ void attn_unit(LAS unsigned char* lds, const int wid, int b, int h, int qb, const bf16_t* __restrict__ Q, const bf16_t* __restrict__ K,
;                                           const bf16_t* __restrict__ V, const bf16_t* __restrict__ ZS, bf16_t* __restrict__ OG) {
;     ...
;         prev_valid = valid;
;         asm volatile("s_waitcnt vmcnt(0)" ::: "memory");
;         __syncthreads();
;     ...
;         int lane_e = lane_id(); asm volatile("" : "+v"(lane_e));
;         const int r32e = lane_e & 31, hie = lane_e >> 5, rowq = lane_e >> 3, c8 = (lane_e & 7) * 8;
;         LAS float* stg = (LAS float*)(lds + 81920 + wid * 8192);
;         const size_t gbase = (tok0 + qw0) * DM + h * HD + c8;
;         u32x4 zv[2][4];
; #pragma unroll
;         for (int ps = 0; ps < 2; ++ps)
; #pragma unroll
;             for (int j = 0; j < 4; ++j) zv[ps][j] = *(const u32x4*)(ZS + gbase + (size_t)(8 * j + rowq) * DM + 64 * ps);
.LBB0_626:
	s_waitcnt vmcnt(0)
	s_xor_b32 s67, s67, 1
	s_add_i32 s42, s42, -1
	s_sub_i32 s66, s66, 64
	v_cmp_gt_f32_e32 vcc, 0x43000000, v158
	s_lshr_b32 s98, s54, 3
	s_lshl_b32 s99, s67, 5
	s_add_i32 s98, s98, s99
	s_add_i32 s98, s98, 0x24000
	s_cmp_lg_u64 vcc, 0
	s_cselect_b32 s99, 1, 0
	s_xor_b32 s75, s99, 1
	s_add_i32 s74, s74, s75
	v_mov_b32_e32 v80, s98
	v_mov_b32_e32 v81, s99
	s_mov_b64 s[100:101], exec
	s_mov_b64 exec, 1
	ds_write_b32 v80, v81
	s_mov_b64 exec, s[100:101]
	s_cmp_lg_u32 s42, -2
	s_waitcnt vmcnt(0) lgkmcnt(0)
	s_barrier
	s_cbranch_scc0 .LBB0_593
	s_add_i32 s32, s32, 1
	s_cmp_lt_u32 s32, 5
	s_cbranch_scc0 .Lvote_do_b
	s_cmp_lg_u32 s32, 3
	s_cbranch_scc1 .Lvote_skip_b
	s_add_u32 s98, s50, s63
	s_addc_u32 s99, s51, 0
	s_lshl_b64 s[98:99], s[98:99], 11
	v_lshlrev_b32_e32 v244, 3, v195
	v_and_b32_e32 v244, 56, v244
	v_or_b32_e32 v244, s98, v244
	v_or_b32_e32 v244, s62, v244
	v_mov_b32_e32 v245, s99
	v_lshlrev_b64 v[244:245], 1, v[244:245]
	v_lshl_add_u64 v[244:245], s[46:47], 0, v[244:245]
	v_ashrrev_i32_e32 v246, 3, v195
	v_mov_b32_e32 v247, 0
	v_lshlrev_b64 v[246:247], 12, v[246:247]
	v_lshl_add_u64 v[244:245], v[244:245], 0, v[246:247]
	s_mov_b32 s100, 0x8000
	s_mov_b32 s101, 0
	global_load_dword v236, v[244:245], off
	global_load_dword v237, v[244:245], off offset:128
	v_lshl_add_u64 v[244:245], v[244:245], 0, s[100:101]
	global_load_dword v238, v[244:245], off
	global_load_dword v239, v[244:245], off offset:128
	v_lshl_add_u64 v[244:245], v[244:245], 0, s[100:101]
	global_load_dword v240, v[244:245], off
	global_load_dword v241, v[244:245], off offset:128
	v_lshl_add_u64 v[244:245], v[244:245], 0, s[100:101]
	global_load_dword v242, v[244:245], off
	global_load_dword v243, v[244:245], off offset:128
	s_branch .Lvote_skip_b
